# attention causal/window masks via v_cmpx exec narrowing (2 ops per element); cmpsel top-k bisection count without wait-state nops
# speedup vs baseline: 1.0515x; 1.0075x over previous
.LBB0_720:
	v_lshl_or_b32 v182, 1, v181, v76
	v_cmp_ge_u32_e32 vcc, v68, v182
	v_cmp_ge_u32_e64 s[0:1], v67, v182
	v_cmp_ge_u32_e64 s[8:9], v69, v182
	v_cndmask_b32_e64 v183, 0, 1, vcc
	v_cmp_ge_u32_e32 vcc, v70, v182
	v_addc_co_u32_e64 v183, s[0:1], 0, v183, s[0:1]
	v_cmp_ge_u32_e64 s[0:1], v71, v182
	v_addc_co_u32_e64 v183, s[8:9], 0, v183, s[8:9]
	v_cmp_ge_u32_e64 s[8:9], v72, v182
	v_addc_co_u32_e32 v183, vcc, 0, v183, vcc
	v_cmp_ge_u32_e32 vcc, v73, v182
	v_addc_co_u32_e64 v183, s[0:1], 0, v183, s[0:1]
	v_cmp_ge_u32_e64 s[0:1], v74, v182
	v_addc_co_u32_e64 v183, s[8:9], 0, v183, s[8:9]
	v_cmp_ge_u32_e64 s[8:9], v75, v182
	v_addc_co_u32_e32 v183, vcc, 0, v183, vcc
	v_cmp_ge_u32_e32 vcc, v77, v182
	v_addc_co_u32_e64 v183, s[0:1], 0, v183, s[0:1]
	v_cmp_ge_u32_e64 s[0:1], v78, v182
	v_addc_co_u32_e64 v183, s[8:9], 0, v183, s[8:9]
	v_cmp_ge_u32_e64 s[8:9], v79, v182
	v_addc_co_u32_e32 v183, vcc, 0, v183, vcc
	v_cmp_ge_u32_e32 vcc, v81, v182
	v_addc_co_u32_e64 v183, s[0:1], 0, v183, s[0:1]
	v_cmp_ge_u32_e64 s[0:1], v82, v182
	v_addc_co_u32_e64 v183, s[8:9], 0, v183, s[8:9]
	v_cmp_ge_u32_e64 s[8:9], v83, v182
	v_addc_co_u32_e32 v183, vcc, 0, v183, vcc
	v_cmp_ge_u32_e32 vcc, v180, v182
	v_addc_co_u32_e64 v183, s[0:1], 0, v183, s[0:1]
	v_addc_co_u32_e64 v183, s[8:9], 0, v183, s[8:9]
	v_addc_co_u32_e32 v183, vcc, 0, v183, vcc
	s_nop 1
	v_add_u32_dpp v183, v183, v183 quad_perm:[1,0,3,2] row_mask:0xf bank_mask:0xf bound_ctrl:1
	s_nop 1
	v_add_u32_dpp v183, v183, v183 quad_perm:[2,3,0,1] row_mask:0xf bank_mask:0xf bound_ctrl:1
	ds_bpermute_b32 v184, v252, v183
	s_waitcnt lgkmcnt(0)
	v_add_u32_e32 v183, v183, v184
	v_cmp_gt_i32_e32 vcc, 13, v183
	s_or_b64 vcc, s[6:7], vcc
	s_nop 0
	v_cndmask_b32_e32 v76, v182, v76, vcc
	v_cmp_eq_u32_e32 vcc, 13, v183
	s_or_b64 s[6:7], s[6:7], vcc
	v_cndmask_b32_e64 v182, 0, 1, s[6:7]
	v_cmp_ne_u32_e32 vcc, 0, v182
	s_cmp_eq_u64 vcc, exec
	v_add_co_u32_e32 v181, vcc, -1, v181
	s_cselect_b64 s[0:1], -1, 0
	s_xor_b64 s[8:9], vcc, -1
	s_or_b64 s[0:1], s[0:1], s[8:9]
	s_and_b64 s[0:1], exec, s[0:1]
	s_or_b64 s[4:5], s[0:1], s[4:5]
	s_andn2_b64 exec, exec, s[4:5]
	s_cbranch_execnz .LBB0_720
	s_or_b64 exec, exec, s[4:5]

.LBB0_817:
	s_add_i32 s0, s42, s47
	s_mov_b32 m0, s0
	s_nop 0
	global_load_lds_dwordx4 v[204:205], off
	s_add_i32 s24, s52, s25
	s_add_i32 s0, s24, -2
	s_cmp_lt_i32 s0, 0
	s_cbranch_scc1 .LBB0_819
	s_mov_b64 s[100:101], exec
	v_sub_u32_e32 v65, v216, v222
	v_subrev_u32_e32 v65, 0xffffff85, v65
	v_cmpx_gt_i32_e32 vcc, 59, v65
	v_mov_b32_e32 v99, v232
	v_cmpx_gt_i32_e32 vcc, 58, v65
	v_mov_b32_e32 v98, v232
	v_cmpx_gt_i32_e32 vcc, 57, v65
	v_mov_b32_e32 v97, v232
	v_cmpx_gt_i32_e32 vcc, 56, v65
	v_mov_b32_e32 v96, v232
	v_cmpx_gt_i32_e32 vcc, 51, v65
	v_mov_b32_e32 v95, v232
	v_cmpx_gt_i32_e32 vcc, 50, v65
	v_mov_b32_e32 v94, v232
	v_cmpx_gt_i32_e32 vcc, 49, v65
	v_mov_b32_e32 v93, v232
	v_cmpx_gt_i32_e32 vcc, 48, v65
	v_mov_b32_e32 v92, v232
	v_cmpx_gt_i32_e32 vcc, 43, v65
	v_mov_b32_e32 v91, v232
	v_cmpx_gt_i32_e32 vcc, 42, v65
	v_mov_b32_e32 v90, v232
	v_cmpx_gt_i32_e32 vcc, 41, v65
	v_mov_b32_e32 v89, v232
	v_cmpx_gt_i32_e32 vcc, 40, v65
	v_mov_b32_e32 v88, v232
	v_cmpx_gt_i32_e32 vcc, 35, v65
	v_mov_b32_e32 v87, v232
	v_cmpx_gt_i32_e32 vcc, 34, v65
	v_mov_b32_e32 v86, v232
	v_cmpx_gt_i32_e32 vcc, 33, v65
	v_mov_b32_e32 v85, v232
	v_cmpx_gt_i32_e32 vcc, 32, v65
	v_mov_b32_e32 v84, v232
	v_cmpx_gt_i32_e32 vcc, 27, v65
	v_mov_b32_e32 v115, v232
	v_cmpx_gt_i32_e32 vcc, 26, v65
	v_mov_b32_e32 v114, v232
	v_cmpx_gt_i32_e32 vcc, 25, v65
	v_mov_b32_e32 v113, v232
	v_cmpx_gt_i32_e32 vcc, 24, v65
	v_mov_b32_e32 v112, v232
	v_cmpx_gt_i32_e32 vcc, 19, v65
	v_mov_b32_e32 v111, v232
	v_cmpx_gt_i32_e32 vcc, 18, v65
	v_mov_b32_e32 v110, v232
	v_cmpx_gt_i32_e32 vcc, 17, v65
	v_mov_b32_e32 v109, v232
	v_cmpx_gt_i32_e32 vcc, 16, v65
	v_mov_b32_e32 v108, v232
	v_cmpx_gt_i32_e32 vcc, 11, v65
	v_mov_b32_e32 v107, v232
	v_cmpx_gt_i32_e32 vcc, 10, v65
	v_mov_b32_e32 v106, v232
	v_cmpx_gt_i32_e32 vcc, 9, v65
	v_mov_b32_e32 v105, v232
	v_cmpx_gt_i32_e32 vcc, 8, v65
	v_mov_b32_e32 v104, v232
	v_cmpx_gt_i32_e32 vcc, 3, v65
	v_mov_b32_e32 v103, v232
	v_cmpx_gt_i32_e32 vcc, 2, v65
	v_mov_b32_e32 v102, v232
	v_cmpx_gt_i32_e32 vcc, 1, v65
	v_mov_b32_e32 v101, v232
	v_cmpx_gt_i32_e32 vcc, 0, v65
	v_mov_b32_e32 v100, v232
	s_mov_b64 exec, s[100:101]

.LBB0_828:
	s_add_i32 s24, s24, -1
	s_cmp_lt_i32 s24, 0
	s_cbranch_scc1 .LBB0_830
	s_mov_b64 s[100:101], exec
	v_sub_u32_e32 v97, v216, v222
	v_subrev_u32_e32 v97, 0xffffffc5, v97
	v_cmpx_gt_i32_e32 vcc, 59, v97
	v_mov_b32_e32 v67, v232
	v_cmpx_gt_i32_e32 vcc, 58, v97
	v_mov_b32_e32 v66, v232
	v_cmpx_gt_i32_e32 vcc, 57, v97
	v_mov_b32_e32 v65, v232
	v_cmpx_gt_i32_e32 vcc, 56, v97
	v_mov_b32_e32 v64, v232
	v_cmpx_gt_i32_e32 vcc, 51, v97
	v_mov_b32_e32 v63, v232
	v_cmpx_gt_i32_e32 vcc, 50, v97
	v_mov_b32_e32 v62, v232
	v_cmpx_gt_i32_e32 vcc, 49, v97
	v_mov_b32_e32 v61, v232
	v_cmpx_gt_i32_e32 vcc, 48, v97
	v_mov_b32_e32 v60, v232
	v_cmpx_gt_i32_e32 vcc, 43, v97
	v_mov_b32_e32 v59, v232
	v_cmpx_gt_i32_e32 vcc, 42, v97
	v_mov_b32_e32 v58, v232
	v_cmpx_gt_i32_e32 vcc, 41, v97
	v_mov_b32_e32 v57, v232
	v_cmpx_gt_i32_e32 vcc, 40, v97
	v_mov_b32_e32 v56, v232
	v_cmpx_gt_i32_e32 vcc, 35, v97
	v_mov_b32_e32 v55, v232
	v_cmpx_gt_i32_e32 vcc, 34, v97
	v_mov_b32_e32 v54, v232
	v_cmpx_gt_i32_e32 vcc, 33, v97
	v_mov_b32_e32 v53, v232
	v_cmpx_gt_i32_e32 vcc, 32, v97
	v_mov_b32_e32 v52, v232
	v_cmpx_gt_i32_e32 vcc, 27, v97
	v_mov_b32_e32 v83, v232
	v_cmpx_gt_i32_e32 vcc, 26, v97
	v_mov_b32_e32 v82, v232
	v_cmpx_gt_i32_e32 vcc, 25, v97
	v_mov_b32_e32 v81, v232
	v_cmpx_gt_i32_e32 vcc, 24, v97
	v_mov_b32_e32 v80, v232
	v_cmpx_gt_i32_e32 vcc, 19, v97
	v_mov_b32_e32 v79, v232
	v_cmpx_gt_i32_e32 vcc, 18, v97
	v_mov_b32_e32 v78, v232
	v_cmpx_gt_i32_e32 vcc, 17, v97
	v_mov_b32_e32 v77, v232
	v_cmpx_gt_i32_e32 vcc, 16, v97
	v_mov_b32_e32 v76, v232
	v_cmpx_gt_i32_e32 vcc, 11, v97
	v_mov_b32_e32 v75, v232
	v_cmpx_gt_i32_e32 vcc, 10, v97
	v_mov_b32_e32 v74, v232
	v_cmpx_gt_i32_e32 vcc, 9, v97
	v_mov_b32_e32 v73, v232
	v_cmpx_gt_i32_e32 vcc, 8, v97
	v_mov_b32_e32 v72, v232
	v_cmpx_gt_i32_e32 vcc, 3, v97
	v_mov_b32_e32 v71, v232
	v_cmpx_gt_i32_e32 vcc, 2, v97
	v_mov_b32_e32 v70, v232
	v_cmpx_gt_i32_e32 vcc, 1, v97
	v_mov_b32_e32 v69, v232
	v_cmpx_gt_i32_e32 vcc, 0, v97
	v_mov_b32_e32 v68, v232
	s_mov_b64 exec, s[100:101]

.LBB0_879:
	v_mov_b32_e32 v52, v0
	s_mov_b32 s25, s65
	v_readfirstlane_b32 s28, v52
	s_ashr_i32 s45, s28, 6
	s_lshl_b32 s47, s45, 5
	s_and_b64 s[0:1], s[22:23], exec
	s_cselect_b32 s24, s18, 0
	s_lshl_b64 s[0:1], s[24:25], 15
	s_add_u32 s0, s0, s26
	s_addc_u32 s1, s1, s27
	s_lshl_b32 s18, s45, 3
	s_ashr_i32 s19, s18, 31
	s_lshl_b32 s46, s45, 10
	s_lshl_b64 s[26:27], s[0:1], 1
	s_add_u32 s0, s55, s26
	s_addc_u32 s1, s56, s27
	v_and_b32_e32 v1, 63, v52
	s_add_u32 s0, s0, s4
	v_lshlrev_b32_e32 v2, 10, v1
	s_addc_u32 s1, s1, s5
	v_and_b32_e32 v218, 31, v52
	v_bfe_u32 v219, v52, 5, 1
	v_mov_b32_e32 v4, v3
	v_lshl_add_u64 v[20:21], s[0:1], 0, v[2:3]
	s_sub_i32 s51, s48, s24
	v_lshlrev_b32_e32 v22, 10, v219
	v_lshlrev_b32_e32 v23, 4, v218
	v_lshl_add_u64 v[206:207], s[18:19], 1, v[20:21]
	v_mov_b32_e32 v18, v4
	v_mov_b32_e32 v19, v4
	s_mov_b64 s[0:1], 0x20000
	s_cmp_lg_u32 0, -1
	v_mov_b32_e32 v5, v4
	v_mov_b32_e32 v6, v4
	v_mov_b32_e32 v7, v4
	v_mov_b32_e32 v8, v4
	v_mov_b32_e32 v9, v4
	v_mov_b32_e32 v10, v4
	v_mov_b32_e32 v11, v4
	v_mov_b32_e32 v12, v4
	v_mov_b32_e32 v13, v4
	v_mov_b32_e32 v14, v4
	v_mov_b32_e32 v15, v4
	v_mov_b32_e32 v16, v4
	v_mov_b32_e32 v17, v4
	v_add3_u32 v246, 0, v22, v23
	v_mov_b64_e32 v[34:35], v[18:19]
	v_lshl_add_u64 v[36:37], v[206:207], 0, s[0:1]
	s_cselect_b32 s0, 0, 0
	v_mov_b64_e32 v[32:33], v[16:17]
	v_mov_b64_e32 v[30:31], v[14:15]
	v_mov_b64_e32 v[28:29], v[12:13]
	v_mov_b64_e32 v[26:27], v[10:11]
	v_mov_b64_e32 v[24:25], v[8:9]
	v_mov_b64_e32 v[22:23], v[6:7]
	v_mov_b64_e32 v[20:21], v[4:5]
	s_add_i32 s0, s0, s46
	s_addk_i32 s0, 0x4000
	s_mov_b32 m0, s0
	s_nop 0
	global_load_lds_dwordx4 v[36:37], off
	s_waitcnt vmcnt(3) lgkmcnt(0)
	s_barrier
	ds_read_b128 v[54:57], v246
	s_waitcnt lgkmcnt(0)
	v_mfma_f32_32x32x16_bf16 v[36:51], v[54:57], v[116:119], v[20:35]
	ds_read_b128 v[54:57], v246 offset:512
	v_or_b32_e32 v204, s47, v218
	s_cmp_gt_i32 s51, 4
	v_lshlrev_b32_e32 v205, 2, v219
	s_waitcnt lgkmcnt(0)
	v_mfma_f32_32x32x16_bf16 v[20:35], v[54:57], v[116:119], v[20:35]
	ds_read_b128 v[54:57], v246 offset:2048
	s_waitcnt lgkmcnt(0)
	v_mfma_f32_32x32x16_bf16 v[36:51], v[54:57], v[120:123], v[36:51]
	ds_read_b128 v[54:57], v246 offset:2560
	s_waitcnt lgkmcnt(0)
	v_mfma_f32_32x32x16_bf16 v[20:35], v[54:57], v[120:123], v[20:35]
	ds_read_b128 v[54:57], v246 offset:4096
	s_waitcnt lgkmcnt(0)
	v_mfma_f32_32x32x16_bf16 v[36:51], v[54:57], v[124:127], v[36:51]
	ds_read_b128 v[54:57], v246 offset:4608
	s_waitcnt lgkmcnt(0)
	v_mfma_f32_32x32x16_bf16 v[20:35], v[54:57], v[124:127], v[20:35]
	ds_read_b128 v[54:57], v246 offset:6144
	s_waitcnt lgkmcnt(0)
	v_mfma_f32_32x32x16_bf16 v[36:51], v[54:57], v[128:131], v[36:51]
	ds_read_b128 v[54:57], v246 offset:6656
	s_waitcnt lgkmcnt(0)
	v_mfma_f32_32x32x16_bf16 v[20:35], v[54:57], v[128:131], v[20:35]
	s_nop 15
	s_nop 7
	s_cbranch_scc1 .LBB0_881
	s_lshl_b32 s0, s51, 6
	s_mov_b64 s[100:101], exec
	v_subrev_u32_e32 v2, s0, v205
	v_sub_u32_e32 v54, v204, v2
	v_subrev_u32_e32 v54, 256, v54
	v_cmpx_gt_i32_e32 vcc, 59, v54
	v_mov_b32_e32 v35, v232
	v_cmpx_gt_i32_e32 vcc, 58, v54
	v_mov_b32_e32 v34, v232
	v_cmpx_gt_i32_e32 vcc, 57, v54
	v_mov_b32_e32 v33, v232
	v_cmpx_gt_i32_e32 vcc, 56, v54
	v_mov_b32_e32 v32, v232
	v_cmpx_gt_i32_e32 vcc, 51, v54
	v_mov_b32_e32 v31, v232
	v_cmpx_gt_i32_e32 vcc, 50, v54
	v_mov_b32_e32 v30, v232
	v_cmpx_gt_i32_e32 vcc, 49, v54
	v_mov_b32_e32 v29, v232
	v_cmpx_gt_i32_e32 vcc, 48, v54
	v_mov_b32_e32 v28, v232
	v_cmpx_gt_i32_e32 vcc, 43, v54
	v_mov_b32_e32 v27, v232
	v_cmpx_gt_i32_e32 vcc, 42, v54
	v_mov_b32_e32 v26, v232
	v_cmpx_gt_i32_e32 vcc, 41, v54
	v_mov_b32_e32 v25, v232
	v_cmpx_gt_i32_e32 vcc, 40, v54
	v_mov_b32_e32 v24, v232
	v_cmpx_gt_i32_e32 vcc, 35, v54
	v_mov_b32_e32 v23, v232
	v_cmpx_gt_i32_e32 vcc, 34, v54
	v_mov_b32_e32 v22, v232
	v_cmpx_gt_i32_e32 vcc, 33, v54
	v_mov_b32_e32 v21, v232
	v_cmpx_gt_i32_e32 vcc, 32, v54
	v_mov_b32_e32 v20, v232
	v_cmpx_gt_i32_e32 vcc, 27, v54
	v_mov_b32_e32 v51, v232
	v_cmpx_gt_i32_e32 vcc, 26, v54
	v_mov_b32_e32 v50, v232
	v_cmpx_gt_i32_e32 vcc, 25, v54
	v_mov_b32_e32 v49, v232
	v_cmpx_gt_i32_e32 vcc, 24, v54
	v_mov_b32_e32 v48, v232
	v_cmpx_gt_i32_e32 vcc, 19, v54
	v_mov_b32_e32 v47, v232
	v_cmpx_gt_i32_e32 vcc, 18, v54
	v_mov_b32_e32 v46, v232
	v_cmpx_gt_i32_e32 vcc, 17, v54
	v_mov_b32_e32 v45, v232
	v_cmpx_gt_i32_e32 vcc, 16, v54
	v_mov_b32_e32 v44, v232
	v_cmpx_gt_i32_e32 vcc, 11, v54
	v_mov_b32_e32 v43, v232
	v_cmpx_gt_i32_e32 vcc, 10, v54
	v_mov_b32_e32 v42, v232
	v_cmpx_gt_i32_e32 vcc, 9, v54
	v_mov_b32_e32 v41, v232
	v_cmpx_gt_i32_e32 vcc, 8, v54
	v_mov_b32_e32 v40, v232
	v_cmpx_gt_i32_e32 vcc, 3, v54
	v_mov_b32_e32 v39, v232
	v_cmpx_gt_i32_e32 vcc, 2, v54
	v_mov_b32_e32 v38, v232
	v_cmpx_gt_i32_e32 vcc, 1, v54
	v_mov_b32_e32 v37, v232
	v_cmpx_gt_i32_e32 vcc, 0, v54
	v_mov_b32_e32 v36, v232
	s_mov_b64 exec, s[100:101]

.LBB0_905:
	s_add_i32 s1, s54, s50
	s_mov_b32 m0, s1
	s_nop 0
	global_load_lds_dwordx4 v[194:195], off
	s_add_i32 s30, s56, s0
	s_add_i32 s1, s30, -2
	s_cmp_lt_i32 s1, 0
	s_cbranch_scc1 .LBB0_907
	s_mov_b64 s[100:101], exec
	v_add_u32_e32 v64, s52, v205
	v_sub_u32_e32 v65, v204, v64
	v_cmpx_gt_i32_e32 vcc, 59, v65
	v_mov_b32_e32 v99, v232
	v_cmpx_gt_i32_e32 vcc, 58, v65
	v_mov_b32_e32 v98, v232
	v_cmpx_gt_i32_e32 vcc, 57, v65
	v_mov_b32_e32 v97, v232
	v_cmpx_gt_i32_e32 vcc, 56, v65
	v_mov_b32_e32 v96, v232
	v_cmpx_gt_i32_e32 vcc, 51, v65
	v_mov_b32_e32 v95, v232
	v_cmpx_gt_i32_e32 vcc, 50, v65
	v_mov_b32_e32 v94, v232
	v_cmpx_gt_i32_e32 vcc, 49, v65
	v_mov_b32_e32 v93, v232
	v_cmpx_gt_i32_e32 vcc, 48, v65
	v_mov_b32_e32 v92, v232
	v_cmpx_gt_i32_e32 vcc, 43, v65
	v_mov_b32_e32 v91, v232
	v_cmpx_gt_i32_e32 vcc, 42, v65
	v_mov_b32_e32 v90, v232
	v_cmpx_gt_i32_e32 vcc, 41, v65
	v_mov_b32_e32 v89, v232
	v_cmpx_gt_i32_e32 vcc, 40, v65
	v_mov_b32_e32 v88, v232
	v_cmpx_gt_i32_e32 vcc, 35, v65
	v_mov_b32_e32 v87, v232
	v_cmpx_gt_i32_e32 vcc, 34, v65
	v_mov_b32_e32 v86, v232
	v_cmpx_gt_i32_e32 vcc, 33, v65
	v_mov_b32_e32 v85, v232
	v_cmpx_gt_i32_e32 vcc, 32, v65
	v_mov_b32_e32 v84, v232
	v_cmpx_gt_i32_e32 vcc, 27, v65
	v_mov_b32_e32 v115, v232
	v_cmpx_gt_i32_e32 vcc, 26, v65
	v_mov_b32_e32 v114, v232
	v_cmpx_gt_i32_e32 vcc, 25, v65
	v_mov_b32_e32 v113, v232
	v_cmpx_gt_i32_e32 vcc, 24, v65
	v_mov_b32_e32 v112, v232
	v_cmpx_gt_i32_e32 vcc, 19, v65
	v_mov_b32_e32 v111, v232
	v_cmpx_gt_i32_e32 vcc, 18, v65
	v_mov_b32_e32 v110, v232
	v_cmpx_gt_i32_e32 vcc, 17, v65
	v_mov_b32_e32 v109, v232
	v_cmpx_gt_i32_e32 vcc, 16, v65
	v_mov_b32_e32 v108, v232
	v_cmpx_gt_i32_e32 vcc, 11, v65
	v_mov_b32_e32 v107, v232
	v_cmpx_gt_i32_e32 vcc, 10, v65
	v_mov_b32_e32 v106, v232
	v_cmpx_gt_i32_e32 vcc, 9, v65
	v_mov_b32_e32 v105, v232
	v_cmpx_gt_i32_e32 vcc, 8, v65
	v_mov_b32_e32 v104, v232
	v_cmpx_gt_i32_e32 vcc, 3, v65
	v_mov_b32_e32 v103, v232
	v_cmpx_gt_i32_e32 vcc, 2, v65
	v_mov_b32_e32 v102, v232
	v_cmpx_gt_i32_e32 vcc, 1, v65
	v_mov_b32_e32 v101, v232
	v_cmpx_gt_i32_e32 vcc, 0, v65
	v_mov_b32_e32 v100, v232
	s_mov_b64 exec, s[100:101]

.LBB0_916:
	s_add_i32 s30, s30, -1
	s_cmp_lt_i32 s30, 0
	s_cbranch_scc1 .LBB0_918
	s_mov_b64 s[100:101], exec
	v_add_u32_e32 v93, s55, v205
	v_sub_u32_e32 v95, v204, v93
	v_subrev_u32_e32 v95, 64, v95
	v_cmpx_gt_i32_e32 vcc, 59, v95
	v_mov_b32_e32 v67, v232
	v_cmpx_gt_i32_e32 vcc, 58, v95
	v_mov_b32_e32 v66, v232
	v_cmpx_gt_i32_e32 vcc, 57, v95
	v_mov_b32_e32 v65, v232
	v_cmpx_gt_i32_e32 vcc, 56, v95
	v_mov_b32_e32 v64, v232
	v_cmpx_gt_i32_e32 vcc, 51, v95
	v_mov_b32_e32 v63, v232
	v_cmpx_gt_i32_e32 vcc, 50, v95
	v_mov_b32_e32 v62, v232
	v_cmpx_gt_i32_e32 vcc, 49, v95
	v_mov_b32_e32 v61, v232
	v_cmpx_gt_i32_e32 vcc, 48, v95
	v_mov_b32_e32 v60, v232
	v_cmpx_gt_i32_e32 vcc, 43, v95
	v_mov_b32_e32 v59, v232
	v_cmpx_gt_i32_e32 vcc, 42, v95
	v_mov_b32_e32 v58, v232
	v_cmpx_gt_i32_e32 vcc, 41, v95
	v_mov_b32_e32 v57, v232
	v_cmpx_gt_i32_e32 vcc, 40, v95
	v_mov_b32_e32 v56, v232
	v_cmpx_gt_i32_e32 vcc, 35, v95
	v_mov_b32_e32 v55, v232
	v_cmpx_gt_i32_e32 vcc, 34, v95
	v_mov_b32_e32 v54, v232
	v_cmpx_gt_i32_e32 vcc, 33, v95
	v_mov_b32_e32 v53, v232
	v_cmpx_gt_i32_e32 vcc, 32, v95
	v_mov_b32_e32 v52, v232
	v_cmpx_gt_i32_e32 vcc, 27, v95
	v_mov_b32_e32 v83, v232
	v_cmpx_gt_i32_e32 vcc, 26, v95
	v_mov_b32_e32 v82, v232
	v_cmpx_gt_i32_e32 vcc, 25, v95
	v_mov_b32_e32 v81, v232
	v_cmpx_gt_i32_e32 vcc, 24, v95
	v_mov_b32_e32 v80, v232
	v_cmpx_gt_i32_e32 vcc, 19, v95
	v_mov_b32_e32 v79, v232
	v_cmpx_gt_i32_e32 vcc, 18, v95
	v_mov_b32_e32 v78, v232
	v_cmpx_gt_i32_e32 vcc, 17, v95
	v_mov_b32_e32 v77, v232
	v_cmpx_gt_i32_e32 vcc, 16, v95
	v_mov_b32_e32 v76, v232
	v_cmpx_gt_i32_e32 vcc, 11, v95
	v_mov_b32_e32 v75, v232
	v_cmpx_gt_i32_e32 vcc, 10, v95
	v_mov_b32_e32 v74, v232
	v_cmpx_gt_i32_e32 vcc, 9, v95
	v_mov_b32_e32 v73, v232
	v_cmpx_gt_i32_e32 vcc, 8, v95
	v_mov_b32_e32 v72, v232
	v_cmpx_gt_i32_e32 vcc, 3, v95
	v_mov_b32_e32 v71, v232
	v_cmpx_gt_i32_e32 vcc, 2, v95
	v_mov_b32_e32 v70, v232
	v_cmpx_gt_i32_e32 vcc, 1, v95
	v_mov_b32_e32 v69, v232
	v_cmpx_gt_i32_e32 vcc, 0, v95
	v_mov_b32_e32 v68, v232
	s_mov_b64 exec, s[100:101]

	.amdhsa_kernel _Z6mk_fwd4Args
		.amdhsa_group_segment_fixed_size 0
		.amdhsa_private_segment_fixed_size 0
		.amdhsa_kernarg_size 496
		.amdhsa_user_sgpr_count 2
		.amdhsa_user_sgpr_dispatch_ptr 0
		.amdhsa_user_sgpr_queue_ptr 0
		.amdhsa_user_sgpr_kernarg_segment_ptr 1
		.amdhsa_user_sgpr_dispatch_id 0
		.amdhsa_user_sgpr_kernarg_preload_length 0
		.amdhsa_user_sgpr_kernarg_preload_offset 0
		.amdhsa_user_sgpr_private_segment_size 0
		.amdhsa_uses_dynamic_stack 0
		.amdhsa_enable_private_segment 0
		.amdhsa_system_sgpr_workgroup_id_x 1
		.amdhsa_system_sgpr_workgroup_id_y 0
		.amdhsa_system_sgpr_workgroup_id_z 0
		.amdhsa_system_sgpr_workgroup_info 0
		.amdhsa_system_vgpr_workitem_id 0
		.amdhsa_next_free_vgpr 256
		.amdhsa_next_free_sgpr 102
		.amdhsa_accum_offset 256
		.amdhsa_reserve_vcc 1
		.amdhsa_float_round_mode_32 0
		.amdhsa_float_round_mode_16_64 0
		.amdhsa_float_denorm_mode_32 3
		.amdhsa_float_denorm_mode_16_64 3
		.amdhsa_dx10_clamp 1
		.amdhsa_ieee_mode 1
		.amdhsa_fp16_overflow 0
		.amdhsa_tg_split 0
		.amdhsa_exception_fp_ieee_invalid_op 0
		.amdhsa_exception_fp_denorm_src 0
		.amdhsa_exception_fp_ieee_div_zero 0
		.amdhsa_exception_fp_ieee_overflow 0
		.amdhsa_exception_fp_ieee_underflow 0
		.amdhsa_exception_fp_ieee_inexact 0
		.amdhsa_exception_int_div_zero 0
	.end_amdhsa_kernel

amdhsa.kernels:
  - .agpr_count:     0
    .args:
      - .offset:         0
        .size:           240
        .value_kind:     by_value
      - .offset:         240
        .size:           4
        .value_kind:     hidden_block_count_x
      - .offset:         244
        .size:           4
        .value_kind:     hidden_block_count_y
      - .offset:         248
        .size:           4
        .value_kind:     hidden_block_count_z
      - .offset:         252
        .size:           2
        .value_kind:     hidden_group_size_x
      - .offset:         254
        .size:           2
        .value_kind:     hidden_group_size_y
      - .offset:         256
        .size:           2
        .value_kind:     hidden_group_size_z
      - .offset:         258
        .size:           2
        .value_kind:     hidden_remainder_x
      - .offset:         260
        .size:           2
        .value_kind:     hidden_remainder_y
      - .offset:         262
        .size:           2
        .value_kind:     hidden_remainder_z
      - .offset:         280
        .size:           8
        .value_kind:     hidden_global_offset_x
      - .offset:         288
        .size:           8
        .value_kind:     hidden_global_offset_y
      - .offset:         296
        .size:           8
        .value_kind:     hidden_global_offset_z
      - .offset:         304
        .size:           2
        .value_kind:     hidden_grid_dims
      - .offset:         360
        .size:           4
        .value_kind:     hidden_dynamic_lds_size
    .group_segment_fixed_size: 0
    .kernarg_segment_align: 8
    .kernarg_segment_size: 496
    .language:       OpenCL C
    .language_version:
      - 2
      - 0
    .max_flat_workgroup_size: 512
    .name:           _Z6mk_fwd4Args
    .private_segment_fixed_size: 0
    .sgpr_count:     108
    .sgpr_spill_count: 116
    .symbol:         _Z6mk_fwd4Args.kd
    .uniform_work_group_size: 1
    .uses_dynamic_stack: false
    .vgpr_count:     256
    .vgpr_spill_count: 0
    .wavefront_size: 64
